# PF epilogue: non-temporal (nt) hint on the 184 MB activation stores
# speedup vs baseline: 1.0285x; 1.0285x over previous
; __device__ __forceinline__ unsigned cvt_pk_bf16(float lo, float hi) { unsigned r; asm volatile("v_cvt_pk_bf16_f32 %0, %1, %2" : "=v"(r) : "v"(lo), "v"(hi)); return r; }
; __device__ __forceinline__ float silu_f(float x) { return x * fast_rcp(1.0f + fast_exp2(-LOG2E * x)); }
;     __device__ __forceinline__ void operator()(const f32x4 (&acc)[2][2][4][2], const Unit& u, int wr, int wc, int fr, int fq) const {
;         const int row0 = u.pm * BM + wr * 64 + fr, col0 = u.pn * HALF + wc * 32 + 8 * fq;
;         float rrv[2][4];
; #pragma unroll
;         for (int ai = 0; ai < 2; ++ai)
; #pragma unroll
;             for (int m = 0; m < 4; ++m) rrv[ai][m] = rs[row0 + ai * HALF + m * 16];
; #pragma unroll
;         for (int ai = 0; ai < 2; ++ai)
; #pragma unroll
;             for (int m = 0; m < 4; ++m) {
;                 const float rr = rrv[ai][m];
;                 const f32x4 g0 = acc[ai][0][m][0] * rr, g1 = acc[ai][0][m][1] * rr, u0 = acc[ai][1][m][0] * rr, u1 = acc[ai][1][m][1] * rr;
;                 u32x4 w;
;                 w.x = cvt_pk_bf16(silu_f(g0[0]) * u0[0], silu_f(g0[1]) * u0[1]); w.y = cvt_pk_bf16(silu_f(g0[2]) * u0[2], silu_f(g0[3]) * u0[3]);
;                 w.z = cvt_pk_bf16(silu_f(g1[0]) * u1[0], silu_f(g1[1]) * u1[1]); w.w = cvt_pk_bf16(silu_f(g1[2]) * u1[2], silu_f(g1[3]) * u1[3]);
;                 *(u32x4*)(act + (size_t)(row0 + ai * HALF + m * 16) * DFF + col0) = w;
;             }
;     }
.LBB0_1553:
	v_lshl_add_u32 v162, s45, 8, v1
	v_ashrrev_i32_e32 v163, 31, v162
	v_lshl_add_u64 v[164:165], v[162:163], 2, s[8:9]
	global_load_dword v166, v[164:165], off
	global_load_dword v142, v[164:165], off offset:704
	v_or_b32_e32 v158, 16, v162
	v_ashrrev_i32_e32 v159, 31, v158
	v_lshl_add_u64 v[148:149], v[158:159], 2, s[8:9]
	global_load_dword v160, v[148:149], off
	v_or_b32_e32 v154, 32, v162
	v_ashrrev_i32_e32 v155, 31, v154
	v_or_b32_e32 v150, 48, v162
	v_lshl_add_u64 v[148:149], v[154:155], 2, s[8:9]
	v_ashrrev_i32_e32 v151, 31, v150
	global_load_dword v156, v[148:149], off
	global_load_dword v146, v[164:165], off offset:576
	v_lshl_add_u64 v[148:149], v[150:151], 2, s[8:9]
	global_load_dword v152, v[148:149], off
	global_load_dword v144, v[164:165], off offset:640
	s_movk_i32 s13, 0x1600
	global_load_dword v148, v[164:165], off offset:512
	v_lshl_or_b32 v164, s43, 7, v145
	v_ashrrev_i32_e32 v165, 31, v164
	v_add_u32_e32 v153, 0x90, v162
	v_add_u32_e32 v149, 0xb0, v162
	v_add_u32_e32 v155, 0x80, v162
	v_add_u32_e32 v151, 0xa0, v162
	s_cmp_eq_u32 s42, s40
	s_waitcnt vmcnt(0)
	v_pk_mul_f32 v[126:127], v[126:127], v[166:167] op_sel_hi:[1,0]
	v_pk_mul_f32 v[168:169], v[116:117], v[166:167] op_sel_hi:[1,0]
	v_pk_mul_f32 v[116:117], v[114:115], v[166:167] op_sel_hi:[1,0]
	v_mul_f32_e32 v114, 0xbfb8aa3b, v126
	v_mul_f32_e32 v115, 0xbfb8aa3b, v127
	v_exp_f32_e32 v114, v114
	v_exp_f32_e32 v115, v115
	v_pk_mul_f32 v[118:119], v[118:119], v[166:167] op_sel_hi:[1,0]
	v_pk_mul_f32 v[128:129], v[128:129], v[166:167] op_sel_hi:[1,0]
	v_add_f32_e32 v114, 1.0, v114
	v_add_f32_e32 v115, 1.0, v115
	v_rcp_f32_e32 v114, v114
	v_rcp_f32_e32 v115, v115
	v_pk_mul_f32 v[120:121], v[120:121], v[166:167] op_sel_hi:[1,0]
	v_pk_mul_f32 v[122:123], v[122:123], v[166:167] op_sel_hi:[1,0]
	v_mul_f32_e32 v114, v126, v114
	v_mul_f32_e32 v115, v127, v115
	v_mul_f32_e32 v114, v118, v114
	v_mul_f32_e32 v115, v119, v115
	v_cvt_pk_bf16_f32 v114, v114, v115
	v_mul_f32_e32 v115, 0xbfb8aa3b, v128
	v_mul_f32_e32 v118, 0xbfb8aa3b, v129
	v_exp_f32_e32 v115, v115
	v_exp_f32_e32 v118, v118
	v_pk_mul_f32 v[124:125], v[124:125], v[166:167] op_sel_hi:[1,0]
	v_pk_mul_f32 v[110:111], v[110:111], v[160:161] op_sel_hi:[1,0]
	v_add_f32_e32 v115, 1.0, v115
	v_add_f32_e32 v118, 1.0, v118
	v_rcp_f32_e32 v115, v115
	v_rcp_f32_e32 v118, v118
	v_pk_mul_f32 v[102:103], v[102:103], v[160:161] op_sel_hi:[1,0]
	v_pk_mul_f32 v[112:113], v[112:113], v[160:161] op_sel_hi:[1,0]
	v_mul_f32_e32 v115, v128, v115
	v_mul_f32_e32 v118, v129, v118
	v_mul_f32_e32 v115, v120, v115
	v_mul_f32_e32 v118, v121, v118
	v_cvt_pk_bf16_f32 v115, v115, v118
	v_mul_f32_e32 v118, 0xbfb8aa3b, v122
	v_exp_f32_e32 v118, v118
	v_lshlrev_b64 v[120:121], 1, v[164:165]
	v_pk_mul_f32 v[104:105], v[104:105], v[160:161] op_sel_hi:[1,0]
	v_pk_mul_f32 v[106:107], v[106:107], v[160:161] op_sel_hi:[1,0]
	v_add_f32_e32 v118, 1.0, v118
	v_rcp_f32_e32 v118, v118
	v_pk_mul_f32 v[98:99], v[98:99], v[160:161] op_sel_hi:[1,0]
	v_pk_mul_f32 v[108:109], v[108:109], v[160:161] op_sel_hi:[1,0]
	v_pk_mul_f32 v[100:101], v[100:101], v[160:161] op_sel_hi:[1,0]
	v_mul_f32_e32 v118, v122, v118
	v_mul_f32_e32 v116, v116, v118
	v_mul_f32_e32 v118, 0xbfb8aa3b, v123
	v_exp_f32_e32 v118, v118
	v_pk_mul_f32 v[94:95], v[94:95], v[156:157] op_sel_hi:[1,0]
	v_pk_mul_f32 v[86:87], v[86:87], v[156:157] op_sel_hi:[1,0]
	v_pk_mul_f32 v[96:97], v[96:97], v[156:157] op_sel_hi:[1,0]
	v_add_f32_e32 v118, 1.0, v118
	v_rcp_f32_e32 v118, v118
	v_pk_mul_f32 v[88:89], v[88:89], v[156:157] op_sel_hi:[1,0]
	v_pk_mul_f32 v[90:91], v[90:91], v[156:157] op_sel_hi:[1,0]
	v_pk_mul_f32 v[92:93], v[92:93], v[156:157] op_sel_hi:[1,0]
	v_mul_f32_e32 v118, v123, v118
	v_mul_f32_e32 v117, v117, v118
	v_cvt_pk_bf16_f32 v116, v116, v117
	v_mul_f32_e32 v117, 0xbfb8aa3b, v124
	v_mul_f32_e32 v118, 0xbfb8aa3b, v125
	v_exp_f32_e32 v117, v117
	v_exp_f32_e32 v118, v118
	v_pk_mul_f32 v[78:79], v[78:79], v[152:153] op_sel_hi:[1,0]
	v_pk_mul_f32 v[70:71], v[70:71], v[152:153] op_sel_hi:[1,0]
	v_add_f32_e32 v117, 1.0, v117
	v_add_f32_e32 v118, 1.0, v118
	v_rcp_f32_e32 v117, v117
	v_rcp_f32_e32 v118, v118
	v_pk_mul_f32 v[80:81], v[80:81], v[152:153] op_sel_hi:[1,0]
	v_pk_mul_f32 v[72:73], v[72:73], v[152:153] op_sel_hi:[1,0]
	v_mul_f32_e32 v117, v124, v117
	v_mul_f32_e32 v118, v125, v118
	v_mul_f32_e32 v117, v168, v117
	v_mul_f32_e32 v118, v169, v118
	v_cvt_pk_bf16_f32 v117, v117, v118
	v_mov_b64_e32 v[118:119], s[6:7]
	v_mad_i64_i32 v[122:123], s[20:21], v162, s13, v[118:119]
	v_lshl_add_u64 v[122:123], v[122:123], 0, v[120:121]
	global_store_dwordx4 v[122:123], v[114:117], off nt
	v_pk_mul_f32 v[74:75], v[74:75], v[152:153] op_sel_hi:[1,0]
	v_pk_mul_f32 v[76:77], v[76:77], v[152:153] op_sel_hi:[1,0]
	v_mul_f32_e32 v114, 0xbfb8aa3b, v110
	v_exp_f32_e32 v114, v114
	v_pk_mul_f32 v[62:63], v[62:63], v[148:149] op_sel_hi:[1,0]
	v_pk_mul_f32 v[54:55], v[54:55], v[148:149] op_sel_hi:[1,0]
	v_pk_mul_f32 v[64:65], v[64:65], v[148:149] op_sel_hi:[1,0]
	v_add_f32_e32 v114, 1.0, v114
	v_rcp_f32_e32 v114, v114
	v_pk_mul_f32 v[56:57], v[56:57], v[148:149] op_sel_hi:[1,0]
	v_pk_mul_f32 v[58:59], v[58:59], v[148:149] op_sel_hi:[1,0]
	v_pk_mul_f32 v[60:61], v[60:61], v[148:149] op_sel_hi:[1,0]
	v_mul_f32_e32 v110, v110, v114
	v_mul_f32_e32 v102, v102, v110
	v_mul_f32_e32 v110, 0xbfb8aa3b, v111
	v_exp_f32_e32 v110, v110
	v_pk_mul_f32 v[46:47], v[46:47], v[146:147] op_sel_hi:[1,0]
	v_pk_mul_f32 v[38:39], v[38:39], v[146:147] op_sel_hi:[1,0]
	v_pk_mul_f32 v[48:49], v[48:49], v[146:147] op_sel_hi:[1,0]
	v_add_f32_e32 v110, 1.0, v110
	v_rcp_f32_e32 v110, v110
	v_pk_mul_f32 v[40:41], v[40:41], v[146:147] op_sel_hi:[1,0]
; __device__ __forceinline__ unsigned cvt_pk_bf16(float lo, float hi) { unsigned r; asm volatile("v_cvt_pk_bf16_f32 %0, %1, %2" : "=v"(r) : "v"(lo), "v"(hi)); return r; }
; __device__ __forceinline__ float silu_f(float x) { return x * fast_rcp(1.0f + fast_exp2(-LOG2E * x)); }
;     __device__ __forceinline__ void operator()(const f32x4 (&acc)[2][2][4][2], const Unit& u, int wr, int wc, int fr, int fq) const {
;         const int row0 = u.pm * BM + wr * 64 + fr, col0 = u.pn * HALF + wc * 32 + 8 * fq;
;         float rrv[2][4];
; #pragma unroll
;         for (int ai = 0; ai < 2; ++ai)
; #pragma unroll
;             for (int m = 0; m < 4; ++m) rrv[ai][m] = rs[row0 + ai * HALF + m * 16];
; #pragma unroll
;         for (int ai = 0; ai < 2; ++ai)
; #pragma unroll
;             for (int m = 0; m < 4; ++m) {
;                 const float rr = rrv[ai][m];
;                 const f32x4 g0 = acc[ai][0][m][0] * rr, g1 = acc[ai][0][m][1] * rr, u0 = acc[ai][1][m][0] * rr, u1 = acc[ai][1][m][1] * rr;
;                 u32x4 w;
;                 w.x = cvt_pk_bf16(silu_f(g0[0]) * u0[0], silu_f(g0[1]) * u0[1]); w.y = cvt_pk_bf16(silu_f(g0[2]) * u0[2], silu_f(g0[3]) * u0[3]);
;                 w.z = cvt_pk_bf16(silu_f(g1[0]) * u1[0], silu_f(g1[1]) * u1[1]); w.w = cvt_pk_bf16(silu_f(g1[2]) * u1[2], silu_f(g1[3]) * u1[3]);
;                 *(u32x4*)(act + (size_t)(row0 + ai * HALF + m * 16) * DFF + col0) = w;
;             }
;     }
	v_pk_mul_f32 v[42:43], v[42:43], v[146:147] op_sel_hi:[1,0]
	v_pk_mul_f32 v[44:45], v[44:45], v[146:147] op_sel_hi:[1,0]
	v_mul_f32_e32 v110, v111, v110
	v_mul_f32_e32 v103, v103, v110
	v_cvt_pk_bf16_f32 v102, v102, v103
	v_mul_f32_e32 v103, 0xbfb8aa3b, v112
	v_exp_f32_e32 v103, v103
	v_pk_mul_f32 v[30:31], v[30:31], v[144:145] op_sel_hi:[1,0]
	v_pk_mul_f32 v[22:23], v[22:23], v[144:145] op_sel_hi:[1,0]
	v_pk_mul_f32 v[32:33], v[32:33], v[144:145] op_sel_hi:[1,0]
	v_add_f32_e32 v103, 1.0, v103
	v_rcp_f32_e32 v103, v103
	v_pk_mul_f32 v[24:25], v[24:25], v[144:145] op_sel_hi:[1,0]
	v_pk_mul_f32 v[26:27], v[26:27], v[144:145] op_sel_hi:[1,0]
	v_pk_mul_f32 v[28:29], v[28:29], v[144:145] op_sel_hi:[1,0]
	v_mul_f32_e32 v103, v112, v103
	v_mul_f32_e32 v103, v104, v103
	v_mul_f32_e32 v104, 0xbfb8aa3b, v113
	v_exp_f32_e32 v104, v104
	v_pk_mul_f32 v[14:15], v[14:15], v[142:143] op_sel_hi:[1,0]
	v_pk_mul_f32 v[6:7], v[6:7], v[142:143] op_sel_hi:[1,0]
	v_pk_mul_f32 v[16:17], v[16:17], v[142:143] op_sel_hi:[1,0]
	v_add_f32_e32 v104, 1.0, v104
	v_rcp_f32_e32 v104, v104
	v_pk_mul_f32 v[8:9], v[8:9], v[142:143] op_sel_hi:[1,0]
	v_pk_mul_f32 v[10:11], v[10:11], v[142:143] op_sel_hi:[1,0]
	v_pk_mul_f32 v[12:13], v[12:13], v[142:143] op_sel_hi:[1,0]
	v_mul_f32_e32 v104, v113, v104
	v_mul_f32_e32 v104, v105, v104
	v_cvt_pk_bf16_f32 v103, v103, v104
	v_mul_f32_e32 v104, 0xbfb8aa3b, v106
	v_exp_f32_e32 v104, v104
	s_nop 0
	v_add_f32_e32 v104, 1.0, v104
	v_rcp_f32_e32 v104, v104
	s_nop 0
	v_mul_f32_e32 v104, v106, v104
	v_mul_f32_e32 v98, v98, v104
	v_mul_f32_e32 v104, 0xbfb8aa3b, v107
	v_exp_f32_e32 v104, v104
	s_nop 0
	v_add_f32_e32 v104, 1.0, v104
	v_rcp_f32_e32 v104, v104
	s_nop 0
	v_mul_f32_e32 v104, v107, v104
	v_mul_f32_e32 v99, v99, v104
	v_cvt_pk_bf16_f32 v104, v98, v99
	v_mul_f32_e32 v98, 0xbfb8aa3b, v108
	v_mul_f32_e32 v99, 0xbfb8aa3b, v109
	v_exp_f32_e32 v98, v98
	v_exp_f32_e32 v99, v99
	v_add_f32_e32 v98, 1.0, v98
	v_add_f32_e32 v99, 1.0, v99
	v_rcp_f32_e32 v98, v98
	v_rcp_f32_e32 v99, v99
	v_mul_f32_e32 v98, v108, v98
	v_mul_f32_e32 v99, v109, v99
	v_mul_f32_e32 v98, v100, v98
	v_mul_f32_e32 v99, v101, v99
	v_cvt_pk_bf16_f32 v105, v98, v99
	v_mad_i64_i32 v[98:99], s[20:21], v158, s13, v[118:119]
	v_lshl_add_u64 v[98:99], v[98:99], 0, v[120:121]
	global_store_dwordx4 v[98:99], v[102:105], off nt
	v_pk_mul_f32 v[98:99], v[84:85], v[156:157] op_sel_hi:[1,0]
	v_pk_mul_f32 v[84:85], v[82:83], v[156:157] op_sel_hi:[1,0]
	v_mul_f32_e32 v82, 0xbfb8aa3b, v94
	v_mul_f32_e32 v83, 0xbfb8aa3b, v95
	v_exp_f32_e32 v82, v82
	v_exp_f32_e32 v83, v83
	v_add_f32_e32 v82, 1.0, v82
	v_add_f32_e32 v83, 1.0, v83
	v_rcp_f32_e32 v82, v82
	v_rcp_f32_e32 v83, v83
	v_mul_f32_e32 v82, v94, v82
	v_mul_f32_e32 v83, v95, v83
	v_mul_f32_e32 v82, v86, v82
	v_mul_f32_e32 v83, v87, v83
	v_cvt_pk_bf16_f32 v82, v82, v83
	v_mul_f32_e32 v83, 0xbfb8aa3b, v96
	v_mul_f32_e32 v86, 0xbfb8aa3b, v97
	v_exp_f32_e32 v83, v83
	v_exp_f32_e32 v86, v86
	v_add_f32_e32 v83, 1.0, v83
	v_add_f32_e32 v86, 1.0, v86
	v_rcp_f32_e32 v83, v83
	v_rcp_f32_e32 v86, v86
	v_mul_f32_e32 v83, v96, v83
	v_mul_f32_e32 v86, v97, v86
	v_mul_f32_e32 v83, v88, v83
	v_mul_f32_e32 v86, v89, v86
	v_cvt_pk_bf16_f32 v83, v83, v86
	v_mul_f32_e32 v86, 0xbfb8aa3b, v90
	v_exp_f32_e32 v86, v86
	s_nop 0
	v_add_f32_e32 v86, 1.0, v86
	v_rcp_f32_e32 v86, v86
	s_nop 0
	v_mul_f32_e32 v86, v90, v86
	v_mul_f32_e32 v84, v84, v86
	v_mul_f32_e32 v86, 0xbfb8aa3b, v91
	v_exp_f32_e32 v86, v86
	s_nop 0
	v_add_f32_e32 v86, 1.0, v86
	v_rcp_f32_e32 v86, v86
	s_nop 0
	v_mul_f32_e32 v86, v91, v86
	v_mul_f32_e32 v85, v85, v86
	v_cvt_pk_bf16_f32 v84, v84, v85
	v_mul_f32_e32 v85, 0xbfb8aa3b, v92
	v_mul_f32_e32 v86, 0xbfb8aa3b, v93
	v_exp_f32_e32 v85, v85
	v_exp_f32_e32 v86, v86
	v_add_f32_e32 v85, 1.0, v85
	v_add_f32_e32 v86, 1.0, v86
	v_rcp_f32_e32 v85, v85
	v_rcp_f32_e32 v86, v86
	v_mul_f32_e32 v85, v92, v85
	v_mul_f32_e32 v86, v93, v86
	v_mul_f32_e32 v85, v98, v85
	v_mul_f32_e32 v86, v99, v86
	v_cvt_pk_bf16_f32 v85, v85, v86
	v_mad_i64_i32 v[86:87], s[20:21], v154, s13, v[118:119]
	v_lshl_add_u64 v[86:87], v[86:87], 0, v[120:121]
	global_store_dwordx4 v[86:87], v[82:85], off nt
	s_nop 1
	v_pk_mul_f32 v[82:83], v[68:69], v[152:153] op_sel_hi:[1,0]
	v_pk_mul_f32 v[68:69], v[66:67], v[152:153] op_sel_hi:[1,0]
	v_mul_f32_e32 v66, 0xbfb8aa3b, v78
	v_mul_f32_e32 v67, 0xbfb8aa3b, v79
	v_exp_f32_e32 v66, v66
	v_exp_f32_e32 v67, v67
	v_add_f32_e32 v66, 1.0, v66
	v_add_f32_e32 v67, 1.0, v67
	v_rcp_f32_e32 v66, v66
	v_rcp_f32_e32 v67, v67
	v_mul_f32_e32 v66, v78, v66
	v_mul_f32_e32 v67, v79, v67
	v_mul_f32_e32 v66, v70, v66
	v_mul_f32_e32 v67, v71, v67
	v_cvt_pk_bf16_f32 v66, v66, v67
	v_mul_f32_e32 v67, 0xbfb8aa3b, v80
	v_mul_f32_e32 v70, 0xbfb8aa3b, v81
	v_exp_f32_e32 v67, v67
	v_exp_f32_e32 v70, v70
	v_add_f32_e32 v67, 1.0, v67
	v_add_f32_e32 v70, 1.0, v70
	v_rcp_f32_e32 v67, v67
	v_rcp_f32_e32 v70, v70
	v_mul_f32_e32 v67, v80, v67
	v_mul_f32_e32 v70, v81, v70
	v_mul_f32_e32 v67, v72, v67
	v_mul_f32_e32 v70, v73, v70
	v_cvt_pk_bf16_f32 v67, v67, v70
	v_mul_f32_e32 v70, 0xbfb8aa3b, v74
	v_exp_f32_e32 v70, v70
	s_nop 0
	v_add_f32_e32 v70, 1.0, v70
	v_rcp_f32_e32 v70, v70
	s_nop 0
	v_mul_f32_e32 v70, v74, v70
	v_mul_f32_e32 v68, v68, v70
	v_mul_f32_e32 v70, 0xbfb8aa3b, v75
	v_exp_f32_e32 v70, v70
	s_nop 0
	v_add_f32_e32 v70, 1.0, v70
	v_rcp_f32_e32 v70, v70
	s_nop 0
	v_mul_f32_e32 v70, v75, v70
	v_mul_f32_e32 v69, v69, v70
	v_cvt_pk_bf16_f32 v68, v68, v69
	v_mul_f32_e32 v69, 0xbfb8aa3b, v76
	v_mul_f32_e32 v70, 0xbfb8aa3b, v77
	v_exp_f32_e32 v69, v69
	v_exp_f32_e32 v70, v70
	v_add_f32_e32 v69, 1.0, v69
	v_add_f32_e32 v70, 1.0, v70
	v_rcp_f32_e32 v69, v69
; __device__ __forceinline__ unsigned cvt_pk_bf16(float lo, float hi) { unsigned r; asm volatile("v_cvt_pk_bf16_f32 %0, %1, %2" : "=v"(r) : "v"(lo), "v"(hi)); return r; }
; __device__ __forceinline__ float silu_f(float x) { return x * fast_rcp(1.0f + fast_exp2(-LOG2E * x)); }
;     __device__ __forceinline__ void operator()(const f32x4 (&acc)[2][2][4][2], const Unit& u, int wr, int wc, int fr, int fq) const {
;         const int row0 = u.pm * BM + wr * 64 + fr, col0 = u.pn * HALF + wc * 32 + 8 * fq;
;         float rrv[2][4];
; #pragma unroll
;         for (int ai = 0; ai < 2; ++ai)
; #pragma unroll
;             for (int m = 0; m < 4; ++m) rrv[ai][m] = rs[row0 + ai * HALF + m * 16];
; #pragma unroll
;         for (int ai = 0; ai < 2; ++ai)
; #pragma unroll
;             for (int m = 0; m < 4; ++m) {
;                 const float rr = rrv[ai][m];
;                 const f32x4 g0 = acc[ai][0][m][0] * rr, g1 = acc[ai][0][m][1] * rr, u0 = acc[ai][1][m][0] * rr, u1 = acc[ai][1][m][1] * rr;
;                 u32x4 w;
;                 w.x = cvt_pk_bf16(silu_f(g0[0]) * u0[0], silu_f(g0[1]) * u0[1]); w.y = cvt_pk_bf16(silu_f(g0[2]) * u0[2], silu_f(g0[3]) * u0[3]);
;                 w.z = cvt_pk_bf16(silu_f(g1[0]) * u1[0], silu_f(g1[1]) * u1[1]); w.w = cvt_pk_bf16(silu_f(g1[2]) * u1[2], silu_f(g1[3]) * u1[3]);
;                 *(u32x4*)(act + (size_t)(row0 + ai * HALF + m * 16) * DFF + col0) = w;
;             }
;     }
	v_rcp_f32_e32 v70, v70
	v_mul_f32_e32 v69, v76, v69
	v_mul_f32_e32 v70, v77, v70
	v_mul_f32_e32 v69, v82, v69
	v_mul_f32_e32 v70, v83, v70
	v_cvt_pk_bf16_f32 v69, v69, v70
	v_mad_i64_i32 v[70:71], s[20:21], v150, s13, v[118:119]
	v_lshl_add_u64 v[70:71], v[70:71], 0, v[120:121]
	global_store_dwordx4 v[70:71], v[66:69], off nt
	s_nop 1
	v_pk_mul_f32 v[66:67], v[52:53], v[148:149] op_sel_hi:[1,0]
	v_pk_mul_f32 v[52:53], v[50:51], v[148:149] op_sel_hi:[1,0]
	v_mul_f32_e32 v50, 0xbfb8aa3b, v62
	v_mul_f32_e32 v51, 0xbfb8aa3b, v63
	v_exp_f32_e32 v50, v50
	v_exp_f32_e32 v51, v51
	v_add_f32_e32 v50, 1.0, v50
	v_add_f32_e32 v51, 1.0, v51
	v_rcp_f32_e32 v50, v50
	v_rcp_f32_e32 v51, v51
	v_mul_f32_e32 v50, v62, v50
	v_mul_f32_e32 v51, v63, v51
	v_mul_f32_e32 v50, v54, v50
	v_mul_f32_e32 v51, v55, v51
	v_cvt_pk_bf16_f32 v50, v50, v51
	v_mul_f32_e32 v51, 0xbfb8aa3b, v64
	v_mul_f32_e32 v54, 0xbfb8aa3b, v65
	v_exp_f32_e32 v51, v51
	v_exp_f32_e32 v54, v54
	v_add_f32_e32 v51, 1.0, v51
	v_add_f32_e32 v54, 1.0, v54
	v_rcp_f32_e32 v51, v51
	v_rcp_f32_e32 v54, v54
	v_mul_f32_e32 v51, v64, v51
	v_mul_f32_e32 v54, v65, v54
	v_mul_f32_e32 v51, v56, v51
	v_mul_f32_e32 v54, v57, v54
	v_cvt_pk_bf16_f32 v51, v51, v54
	v_mul_f32_e32 v54, 0xbfb8aa3b, v58
	v_exp_f32_e32 v54, v54
	s_nop 0
	v_add_f32_e32 v54, 1.0, v54
	v_rcp_f32_e32 v54, v54
	s_nop 0
	v_mul_f32_e32 v54, v58, v54
	v_mul_f32_e32 v52, v52, v54
	v_mul_f32_e32 v54, 0xbfb8aa3b, v59
	v_exp_f32_e32 v54, v54
	s_nop 0
	v_add_f32_e32 v54, 1.0, v54
	v_rcp_f32_e32 v54, v54
	s_nop 0
	v_mul_f32_e32 v54, v59, v54
	v_mul_f32_e32 v53, v53, v54
	v_cvt_pk_bf16_f32 v52, v52, v53
	v_mul_f32_e32 v53, 0xbfb8aa3b, v60
	v_mul_f32_e32 v54, 0xbfb8aa3b, v61
	v_exp_f32_e32 v53, v53
	v_exp_f32_e32 v54, v54
	v_add_f32_e32 v53, 1.0, v53
	v_add_f32_e32 v54, 1.0, v54
	v_rcp_f32_e32 v53, v53
	v_rcp_f32_e32 v54, v54
	v_mul_f32_e32 v53, v60, v53
	v_mul_f32_e32 v54, v61, v54
	v_mul_f32_e32 v53, v66, v53
	v_mul_f32_e32 v54, v67, v54
	v_cvt_pk_bf16_f32 v53, v53, v54
	v_mad_i64_i32 v[54:55], s[20:21], v155, s13, v[118:119]
	v_lshl_add_u64 v[54:55], v[54:55], 0, v[120:121]
	global_store_dwordx4 v[54:55], v[50:53], off nt
	s_nop 1
	v_pk_mul_f32 v[50:51], v[36:37], v[146:147] op_sel_hi:[1,0]
	v_pk_mul_f32 v[36:37], v[34:35], v[146:147] op_sel_hi:[1,0]
	v_mul_f32_e32 v34, 0xbfb8aa3b, v46
	v_mul_f32_e32 v35, 0xbfb8aa3b, v47
	v_exp_f32_e32 v34, v34
	v_exp_f32_e32 v35, v35
	v_add_f32_e32 v34, 1.0, v34
	v_add_f32_e32 v35, 1.0, v35
	v_rcp_f32_e32 v34, v34
	v_rcp_f32_e32 v35, v35
	v_mul_f32_e32 v34, v46, v34
	v_mul_f32_e32 v35, v47, v35
	v_mul_f32_e32 v34, v38, v34
	v_mul_f32_e32 v35, v39, v35
	v_cvt_pk_bf16_f32 v34, v34, v35
	v_mul_f32_e32 v35, 0xbfb8aa3b, v48
	v_mul_f32_e32 v38, 0xbfb8aa3b, v49
	v_exp_f32_e32 v35, v35
	v_exp_f32_e32 v38, v38
	v_add_f32_e32 v35, 1.0, v35
	v_add_f32_e32 v38, 1.0, v38
	v_rcp_f32_e32 v35, v35
	v_rcp_f32_e32 v38, v38
	v_mul_f32_e32 v35, v48, v35
	v_mul_f32_e32 v38, v49, v38
	v_mul_f32_e32 v35, v40, v35
	v_mul_f32_e32 v38, v41, v38
	v_cvt_pk_bf16_f32 v35, v35, v38
	v_mul_f32_e32 v38, 0xbfb8aa3b, v42
	v_exp_f32_e32 v38, v38
	s_nop 0
	v_add_f32_e32 v38, 1.0, v38
	v_rcp_f32_e32 v38, v38
	s_nop 0
	v_mul_f32_e32 v38, v42, v38
	v_mul_f32_e32 v36, v36, v38
	v_mul_f32_e32 v38, 0xbfb8aa3b, v43
	v_exp_f32_e32 v38, v38
	s_nop 0
	v_add_f32_e32 v38, 1.0, v38
	v_rcp_f32_e32 v38, v38
	s_nop 0
	v_mul_f32_e32 v38, v43, v38
	v_mul_f32_e32 v37, v37, v38
	v_cvt_pk_bf16_f32 v36, v36, v37
	v_mul_f32_e32 v37, 0xbfb8aa3b, v44
	v_mul_f32_e32 v38, 0xbfb8aa3b, v45
	v_exp_f32_e32 v37, v37
	v_exp_f32_e32 v38, v38
	v_add_f32_e32 v37, 1.0, v37
	v_add_f32_e32 v38, 1.0, v38
	v_rcp_f32_e32 v37, v37
	v_rcp_f32_e32 v38, v38
	v_mul_f32_e32 v37, v44, v37
	v_mul_f32_e32 v38, v45, v38
	v_mul_f32_e32 v37, v50, v37
	v_mul_f32_e32 v38, v51, v38
	v_cvt_pk_bf16_f32 v37, v37, v38
; __device__ __forceinline__ unsigned cvt_pk_bf16(float lo, float hi) { unsigned r; asm volatile("v_cvt_pk_bf16_f32 %0, %1, %2" : "=v"(r) : "v"(lo), "v"(hi)); return r; }
; __device__ __forceinline__ float silu_f(float x) { return x * fast_rcp(1.0f + fast_exp2(-LOG2E * x)); }
;     __device__ __forceinline__ void operator()(const f32x4 (&acc)[2][2][4][2], const Unit& u, int wr, int wc, int fr, int fq) const {
;         const int row0 = u.pm * BM + wr * 64 + fr, col0 = u.pn * HALF + wc * 32 + 8 * fq;
;         float rrv[2][4];
; #pragma unroll
;         for (int ai = 0; ai < 2; ++ai)
; #pragma unroll
;             for (int m = 0; m < 4; ++m) rrv[ai][m] = rs[row0 + ai * HALF + m * 16];
; #pragma unroll
;         for (int ai = 0; ai < 2; ++ai)
; #pragma unroll
;             for (int m = 0; m < 4; ++m) {
;                 const float rr = rrv[ai][m];
;                 const f32x4 g0 = acc[ai][0][m][0] * rr, g1 = acc[ai][0][m][1] * rr, u0 = acc[ai][1][m][0] * rr, u1 = acc[ai][1][m][1] * rr;
;                 u32x4 w;
;                 w.x = cvt_pk_bf16(silu_f(g0[0]) * u0[0], silu_f(g0[1]) * u0[1]); w.y = cvt_pk_bf16(silu_f(g0[2]) * u0[2], silu_f(g0[3]) * u0[3]);
;                 w.z = cvt_pk_bf16(silu_f(g1[0]) * u1[0], silu_f(g1[1]) * u1[1]); w.w = cvt_pk_bf16(silu_f(g1[2]) * u1[2], silu_f(g1[3]) * u1[3]);
;                 *(u32x4*)(act + (size_t)(row0 + ai * HALF + m * 16) * DFF + col0) = w;
;             }
;     }
	v_mad_i64_i32 v[38:39], s[20:21], v153, s13, v[118:119]
	v_lshl_add_u64 v[38:39], v[38:39], 0, v[120:121]
	global_store_dwordx4 v[38:39], v[34:37], off nt
	s_nop 1
	v_pk_mul_f32 v[34:35], v[20:21], v[144:145] op_sel_hi:[1,0]
	v_pk_mul_f32 v[20:21], v[18:19], v[144:145] op_sel_hi:[1,0]
	v_mul_f32_e32 v18, 0xbfb8aa3b, v30
	v_mul_f32_e32 v19, 0xbfb8aa3b, v31
	v_exp_f32_e32 v18, v18
	v_exp_f32_e32 v19, v19
	v_add_f32_e32 v18, 1.0, v18
	v_add_f32_e32 v19, 1.0, v19
	v_rcp_f32_e32 v18, v18
	v_rcp_f32_e32 v19, v19
	v_mul_f32_e32 v18, v30, v18
	v_mul_f32_e32 v19, v31, v19
	v_mul_f32_e32 v18, v22, v18
	v_mul_f32_e32 v19, v23, v19
	v_cvt_pk_bf16_f32 v18, v18, v19
	v_mul_f32_e32 v19, 0xbfb8aa3b, v32
	v_mul_f32_e32 v22, 0xbfb8aa3b, v33
	v_exp_f32_e32 v19, v19
	v_exp_f32_e32 v22, v22
	v_add_f32_e32 v19, 1.0, v19
	v_add_f32_e32 v22, 1.0, v22
	v_rcp_f32_e32 v19, v19
	v_rcp_f32_e32 v22, v22
	v_mul_f32_e32 v19, v32, v19
	v_mul_f32_e32 v22, v33, v22
	v_mul_f32_e32 v19, v24, v19
	v_mul_f32_e32 v22, v25, v22
	v_cvt_pk_bf16_f32 v19, v19, v22
	v_mul_f32_e32 v22, 0xbfb8aa3b, v26
	v_exp_f32_e32 v22, v22
	s_nop 0
	v_add_f32_e32 v22, 1.0, v22
	v_rcp_f32_e32 v22, v22
	s_nop 0
	v_mul_f32_e32 v22, v26, v22
	v_mul_f32_e32 v20, v20, v22
	v_mul_f32_e32 v22, 0xbfb8aa3b, v27
	v_exp_f32_e32 v22, v22
	s_nop 0
	v_add_f32_e32 v22, 1.0, v22
	v_rcp_f32_e32 v22, v22
	s_nop 0
	v_mul_f32_e32 v22, v27, v22
	v_mul_f32_e32 v21, v21, v22
	v_cvt_pk_bf16_f32 v20, v20, v21
	v_mul_f32_e32 v21, 0xbfb8aa3b, v28
	v_mul_f32_e32 v22, 0xbfb8aa3b, v29
	v_exp_f32_e32 v21, v21
	v_exp_f32_e32 v22, v22
	v_add_f32_e32 v21, 1.0, v21
	v_add_f32_e32 v22, 1.0, v22
	v_rcp_f32_e32 v21, v21
	v_rcp_f32_e32 v22, v22
	v_mul_f32_e32 v21, v28, v21
	v_mul_f32_e32 v22, v29, v22
	v_mul_f32_e32 v21, v34, v21
	v_mul_f32_e32 v22, v35, v22
	v_cvt_pk_bf16_f32 v21, v21, v22
	v_mad_i64_i32 v[22:23], s[20:21], v151, s13, v[118:119]
	v_lshl_add_u64 v[22:23], v[22:23], 0, v[120:121]
	global_store_dwordx4 v[22:23], v[18:21], off nt
	s_nop 1
	v_pk_mul_f32 v[18:19], v[4:5], v[142:143] op_sel_hi:[1,0]
	v_pk_mul_f32 v[4:5], v[2:3], v[142:143] op_sel_hi:[1,0]
	v_mul_f32_e32 v2, 0xbfb8aa3b, v14
	v_mul_f32_e32 v3, 0xbfb8aa3b, v15
	v_exp_f32_e32 v2, v2
	v_exp_f32_e32 v3, v3
	v_add_f32_e32 v2, 1.0, v2
	v_add_f32_e32 v3, 1.0, v3
	v_rcp_f32_e32 v2, v2
	v_rcp_f32_e32 v3, v3
	v_mul_f32_e32 v2, v14, v2
	v_mul_f32_e32 v3, v15, v3
	v_mul_f32_e32 v2, v6, v2
	v_mul_f32_e32 v3, v7, v3
	v_cvt_pk_bf16_f32 v2, v2, v3
	v_mul_f32_e32 v3, 0xbfb8aa3b, v16
	v_mul_f32_e32 v6, 0xbfb8aa3b, v17
	v_exp_f32_e32 v3, v3
	v_exp_f32_e32 v6, v6
	v_add_f32_e32 v3, 1.0, v3
	v_add_f32_e32 v6, 1.0, v6
	v_rcp_f32_e32 v3, v3
	v_rcp_f32_e32 v6, v6
	v_mul_f32_e32 v3, v16, v3
	v_mul_f32_e32 v6, v17, v6
	v_mul_f32_e32 v3, v8, v3
	v_mul_f32_e32 v6, v9, v6
	v_cvt_pk_bf16_f32 v3, v3, v6
	v_mul_f32_e32 v6, 0xbfb8aa3b, v10
	v_exp_f32_e32 v6, v6
	s_nop 0
	v_add_f32_e32 v6, 1.0, v6
	v_rcp_f32_e32 v6, v6
	s_nop 0
	v_mul_f32_e32 v6, v10, v6
	v_mul_f32_e32 v4, v4, v6
	v_mul_f32_e32 v6, 0xbfb8aa3b, v11
	v_exp_f32_e32 v6, v6
	s_nop 0
	v_add_f32_e32 v6, 1.0, v6
	v_rcp_f32_e32 v6, v6
	s_nop 0
	v_mul_f32_e32 v6, v11, v6
	v_mul_f32_e32 v5, v5, v6
	v_cvt_pk_bf16_f32 v4, v4, v5
	v_mul_f32_e32 v5, 0xbfb8aa3b, v12
	v_mul_f32_e32 v6, 0xbfb8aa3b, v13
	v_exp_f32_e32 v5, v5
	v_exp_f32_e32 v6, v6
	v_add_f32_e32 v5, 1.0, v5
	v_add_f32_e32 v6, 1.0, v6
	v_rcp_f32_e32 v5, v5
	v_rcp_f32_e32 v6, v6
	v_mul_f32_e32 v5, v12, v5
	v_mul_f32_e32 v6, v13, v6
	v_mul_f32_e32 v5, v18, v5
	v_mul_f32_e32 v6, v19, v6
	v_cvt_pk_bf16_f32 v5, v5, v6
	v_mad_i64_i32 v[6:7], s[20:21], v149, s13, v[118:119]
	v_lshl_add_u64 v[6:7], v[6:7], 0, v[120:121]
	s_mov_b64 s[20:21], -1
	global_store_dwordx4 v[6:7], v[2:5], off nt
	s_cbranch_scc1 .LBB0_1546
	s_andn2_b64 vcc, exec, s[4:5]
	s_cbranch_vccnz .LBB0_1545
	s_barrier
	s_branch .LBB0_1545
